# SSD-B intra-chunk loop: first operand batch of each inner iteration prefetched one iteration ahead (no exposed load wait at the loop top)
# baseline (speedup 1.0000x reference)
.LBB0_931:
	s_lshl_b32 s1, s0, 7
	s_and_b32 s18, s1, 0xffffff00
	v_lshl_add_u64 v[2:3], v[70:71], 0, s[18:19]
	global_load_dwordx4 v[14:17], v[2:3], off offset:512
	global_load_dwordx4 v[10:13], v[2:3], off offset:576
	global_load_dwordx4 v[6:9], v[2:3], off offset:640
	s_nop 0
	global_load_dwordx4 v[2:5], v[2:3], off offset:704
	v_lshl_add_u32 v0, s0, 2, v108
	ds_read2_b32 v[88:89], v0 offset1:4
	s_lshl_b64 s[4:5], s[8:9], 1
	s_and_b32 s4, s4, 0xffffff00
	v_lshl_add_u64 v[54:55], v[84:85], 0, s[4:5]
	s_lshl_b32 s1, s0, 6
	v_mov_b64_e32 v[56:57], v[86:87]
	v_mov_b32_e32 v0, v111
	s_mov_b32 s4, 0
	v_mov_b32_e32 v30, 0
	v_mov_b32_e32 v31, v112
	v_mov_b32_e32 v32, v112
	v_mov_b32_e32 v33, v112
	v_mov_b32_e32 v26, 0
	v_mov_b32_e32 v27, v112
	v_mov_b32_e32 v28, v112
	v_mov_b32_e32 v29, v112
	v_mov_b32_e32 v22, 0
	v_mov_b32_e32 v23, v112
	v_mov_b32_e32 v24, v112
	v_mov_b32_e32 v25, v112
	v_mov_b32_e32 v18, 0
	v_mov_b32_e32 v19, v112
	v_mov_b32_e32 v20, v112
	v_mov_b32_e32 v21, v112
	v_lshl_add_u64 v[150:151], s[6:7], 0, v[54:55]
	v_add_co_u32_e32 v150, vcc, s73, v150
	s_nop 0
	v_addc_co_u32_e32 v151, vcc, 0, v151, vcc
	global_load_dwordx4 v[134:137], v[150:151], off
	global_load_dwordx4 v[138:141], v[150:151], off offset:64
	global_load_dwordx4 v[142:145], v[150:151], off offset:128
	global_load_dwordx4 v[146:149], v[150:151], off offset:192
	s_branch .LBB0_933

.LBB0_933:
	v_lshl_add_u64 v[38:39], s[6:7], 0, v[54:55]
	v_add_co_u32_e32 v40, vcc, s73, v38
	v_lshl_add_u64 v[42:43], s[6:7], 0, v[56:57]
	s_nop 0
	v_addc_co_u32_e32 v41, vcc, 0, v39, vcc
	v_lshl_add_u64 v[150:151], v[40:41], 0, s[16:17]
	v_add_co_u32_e32 v94, vcc, s66, v42
	s_nop 0
	v_addc_co_u32_e32 v95, vcc, 0, v43, vcc
	v_add_co_u32_e32 v98, vcc, s67, v42
	v_mov_b32_e32 v116, 0xff800000
	s_nop 0
	v_addc_co_u32_e32 v99, vcc, 0, v43, vcc
	v_add_co_u32_e32 v102, vcc, s68, v42
	s_waitcnt vmcnt(0) lgkmcnt(0)
	v_mfma_f32_16x16x32_bf16 v[58:61], v[134:137], v[14:17], 0
	v_addc_co_u32_e32 v103, vcc, 0, v43, vcc
	v_add_co_u32_e32 v114, vcc, s69, v42
	v_mfma_f32_16x16x32_bf16 v[50:53], v[138:141], v[10:13], v[58:61]
	s_nop 0
	v_addc_co_u32_e32 v115, vcc, 0, v43, vcc
	v_add_co_u32_e32 v46, vcc, s74, v38
	v_mfma_f32_16x16x32_bf16 v[50:53], v[142:145], v[6:9], v[50:53]
	s_nop 0
	v_addc_co_u32_e32 v47, vcc, 0, v39, vcc
	global_load_dwordx4 v[34:37], v[46:47], off
	global_load_dwordx4 v[38:41], v[46:47], off offset:64
	global_load_dwordx4 v[42:45], v[46:47], off offset:128
	s_nop 0
	global_load_dwordx4 v[46:49], v[46:47], off offset:192
	s_nop 0
	global_load_dwordx2 v[100:101], v[94:95], off
	global_load_dwordx2 v[96:97], v[98:99], off
	global_load_dwordx2 v[58:59], v[98:99], off offset:32
	global_load_dwordx2 v[60:61], v[94:95], off offset:32
	s_nop 0
	global_load_dwordx2 v[98:99], v[102:103], off
	global_load_dwordx2 v[94:95], v[114:115], off
	global_load_dwordx2 v[90:91], v[114:115], off offset:32
	global_load_dwordx2 v[92:93], v[102:103], off offset:32
	v_mfma_f32_16x16x32_bf16 v[50:53], v[146:149], v[2:5], v[50:53]
	global_load_dwordx4 v[134:137], v[150:151], off
	global_load_dwordx4 v[138:141], v[150:151], off offset:64
	global_load_dwordx4 v[142:145], v[150:151], off offset:128
	global_load_dwordx4 v[146:149], v[150:151], off offset:192
	v_subrev_u32_e32 v102, 19, v0
	v_cmp_le_i32_e32 vcc, v102, v68
	v_mov_b32_e32 v115, 0xff800000
	v_add_u32_e32 v114, s4, v110
	s_and_saveexec_b64 s[12:13], vcc
	s_cbranch_execz .LBB0_935
	v_add_u32_e32 v103, 0x20000, v114
	ds_read_b32 v103, v103
	s_waitcnt lgkmcnt(0)
	v_sub_f32_e32 v103, v88, v103
	v_mul_f32_e32 v116, 0x3fb8aa3b, v103

.LBB0_949:
	s_or_b64 exec, exec, s[12:13]
	v_exp_f32_e32 v124, v116
	v_exp_f32_e32 v125, v115
	v_exp_f32_e32 v116, v119
	v_exp_f32_e32 v117, v117
	s_waitcnt vmcnt(4) lgkmcnt(0)
	v_mfma_f32_16x16x32_bf16 v[34:37], v[34:37], v[14:17], 0
	v_mul_f32_e64 v102, v124, v102
	v_mul_f32_e64 v103, v125, v103
	v_add_f32_e32 v102, v102, v103
	v_mul_f32_e32 v50, v50, v102
	v_pk_mul_f32 v[102:103], v[116:117], v[104:105]
	v_exp_f32_e32 v104, v121
	v_exp_f32_e32 v105, v120
	v_cvt_pk_bf16_f32 v115, v50, s0
	v_add_f32_e32 v50, v102, v103
	v_mul_f32_e32 v50, v51, v50
	v_cvt_pk_bf16_f32 v116, v50, s0
	v_pk_mul_f32 v[50:51], v[104:105], v[106:107]
	v_add_u32_e32 v103, 0x21060, v114
	v_add_u32_e32 v105, 0x21070, v114
	ds_read_b32 v104, v103
	ds_read_b32 v105, v105
	v_exp_f32_e32 v102, v122
	v_exp_f32_e32 v103, v118
	v_mfma_f32_16x16x32_bf16 v[34:37], v[38:41], v[10:13], v[34:37]
	v_add_f32_e32 v50, v50, v51
	v_mul_f32_e32 v50, v52, v50
	v_cvt_pk_bf16_f32 v52, v50, s0
	s_waitcnt lgkmcnt(0)
	v_pk_mul_f32 v[50:51], v[102:103], v[104:105]
	v_mfma_f32_16x16x32_bf16 v[34:37], v[42:45], v[6:9], v[34:37]
	v_add_f32_e32 v50, v50, v51
	v_mul_f32_e32 v50, v53, v50
	v_cvt_pk_bf16_f32 v51, v50, s0
	v_perm_b32 v50, v116, v115, s75
	v_perm_b32 v51, v51, v52, s75
	v_mfma_f32_16x16x32_bf16 v[34:37], v[46:49], v[2:5], v[34:37]
	v_add_u32_e32 v38, -3, v0
	v_cmp_le_i32_e32 vcc, v38, v68
	v_mov_b32_e32 v44, 0xff800000
	v_mfma_f32_16x16x16_bf16 v[30:33], v[100:101], v[50:51], v[30:33]
	v_mov_b32_e32 v45, 0xff800000
	v_mfma_f32_16x16x16_bf16 v[26:29], v[96:97], v[50:51], v[26:29]
	v_mfma_f32_16x16x16_bf16 v[22:25], v[98:99], v[50:51], v[22:25]
	v_mfma_f32_16x16x16_bf16 v[18:21], v[94:95], v[50:51], v[18:21]
	s_and_saveexec_b64 s[12:13], vcc
	s_cbranch_execz .LBB0_951
	v_add_u32_e32 v39, 0x20200, v114
	ds_read_b32 v39, v39
	s_waitcnt lgkmcnt(0)
	v_sub_f32_e32 v39, v88, v39
	v_mul_f32_e32 v45, 0x3fb8aa3b, v39
